# same as previous best, DA bias-table reuse now conditional on gridDim==256 (placement-independent)
# baseline (speedup 1.0000x reference)
; __device__ __forceinline__ void diff_attn_phase(const Params& p, int j, int layer_idx, char* shm, int wv) {
;     ...
;     __syncthreads();
;     if (tid < 128) btab[tid] = p.biastab[h * 128 + tid];
.LBB0_1778:
	s_lshl_b32 s6, s28, 7
	s_and_b32 s9, s6, 0x380
	s_barrier
	s_cmp_eq_u32 s70, 0x100
	s_cselect_b64 vcc, s[0:1], 0
	s_andn2_b64 vcc, s[4:5], vcc
	s_and_saveexec_b64 s[6:7], vcc
	s_cbranch_execz .LBB0_1780
	v_add_u32_e32 v0, s9, v186
	v_ashrrev_i32_e32 v1, 31, v0
	v_lshl_add_u64 v[0:1], v[0:1], 2, s[10:11]
	global_load_dword v0, v[0:1], off
	s_waitcnt vmcnt(0)
	ds_write_b32 v187, v0
